# v003 + P1 (QKV) epilogue: rs1/rope loads prefetched into dead fragment VGPRs, counted vmcnt instead of 8 serialized vmcnt(0)
# speedup vs baseline: 1.0019x; 1.0019x over previous
; __device__ __forceinline__ u32x4 pack8(f32x4 a, f32x4 b) { u32x4 w; w.x = cvt_pk_bf16(a[0], a[1]); w.y = cvt_pk_bf16(a[2], a[3]); w.z = cvt_pk_bf16(b[0], b[1]); w.w = cvt_pk_bf16(b[2], b[3]); return w; }
;     __device__ __forceinline__ void operator()(const f32x4 (&acc)[2][2][4][2], const Unit& u, int wr, int wc, int fr, int fq) const {
;     ...
;         const bool rl = (part < 2) && ((wc & 1) == 0) && (fq < 2);
;         const int row0 = u.pm * BM + wr * 64 + fr, col0 = colt + wc * 32 + 8 * fq;
; #pragma unroll
;         for (int ai = 0; ai < 2; ++ai)
; #pragma unroll
;             for (int m = 0; m < 4; ++m) {
;                 const int row = row0 + ai * HALF + m * 16;
;                 const float rs = rs1[row] * sc;
;                 f32x4 cs = (f32x4){1.f, 1.f, 1.f, 1.f}, sn = (f32x4){0.f, 0.f, 0.f, 0.f};
;                 if (rl) { const float* rp = rope + (size_t)(row & (SEQ - 1)) * 16 + 4 * fq; cs = *(const f32x4*)rp; sn = *(const f32x4*)(rp + 8); }
;                 bf16_t* rowp = base + (size_t)row * ldc + col0;
; #pragma unroll
;                 for (int bj = 0; bj < 2; ++bj) {
;                     const f32x4 v0 = acc[ai][bj][m][0], v1 = acc[ai][bj][m][1];
;                     const f32x4 o0 = (v0 * cs - v1 * sn) * rs, o1 = (v1 * cs + v0 * sn) * rs;
;                     *(u32x4*)(rowp + bj * HALF) = pack8(o0, o1);
.LBB0_398:
	v_lshl_add_u32 v162, s72, 8, v168
	v_ashrrev_i32_e32 v163, 31, v162
	v_lshl_add_u64 v[164:165], v[162:163], 2, s[0:1]
	global_load_dword v129, v[164:165], off
	global_load_dword v181, v[164:165], off offset:64
	global_load_dword v182, v[164:165], off offset:128
	global_load_dword v183, v[164:165], off offset:192
	global_load_dword v184, v[164:165], off offset:512
	global_load_dword v185, v[164:165], off offset:576
	global_load_dword v186, v[164:165], off offset:640
	global_load_dword v187, v[164:165], off offset:704
	s_cmp_lt_i32 s70, 12
	s_cselect_b64 s[14:15], -1, 0
	s_and_b64 s[14:15], s[62:63], s[14:15]
	s_and_b64 s[72:73], s[14:15], s[2:3]
	v_mov_b32_e32 v128, 1.0
	v_mov_b32_e32 v132, 0
	v_mov_b32_e32 v134, 0
	v_mov_b32_e32 v135, 0
	v_mov_b32_e32 v136, 0
	v_mov_b32_e32 v137, 0
	v_mov_b32_e32 v138, 1.0
	v_mov_b32_e32 v139, 1.0
	v_mov_b32_e32 v140, 1.0
	v_mov_b32_e32 v141, 1.0
	s_and_saveexec_b64 s[78:79], s[72:73]
	s_cbranch_execz .LBB0_400
	v_lshlrev_b32_e32 v130, 6, v162
	v_and_b32_e32 v150, 0x7f3c0, v130
	v_lshl_add_u64 v[130:131], v[152:153], 0, v[150:151]
	global_load_dwordx4 v[138:141], v[130:131], off
	global_load_dwordx4 v[134:137], v[130:131], off offset:32
	global_load_dwordx4 v[196:199], v[130:131], off offset:1024
	global_load_dwordx4 v[200:203], v[130:131], off offset:1056
	global_load_dwordx4 v[208:211], v[130:131], off offset:2048
	global_load_dwordx4 v[212:215], v[130:131], off offset:2080
	global_load_dwordx4 v[216:219], v[130:131], off offset:3072
	global_load_dwordx4 v[220:223], v[130:131], off offset:3104
.LBB0_400:
	s_or_b64 exec, exec, s[78:79]
	s_mul_i32 s14, s33, -6
	s_add_i32 s14, s14, s70
	v_lshl_or_b32 v130, s14, 8, v170
	v_ashrrev_i32_e32 v131, 31, v130
	s_waitcnt vmcnt(0)
	v_pk_mul_f32 v[176:177], v[122:123], v[136:137]
	v_pk_mul_f32 v[178:179], v[120:121], v[134:135]
	v_pk_mul_f32 v[122:123], v[122:123], v[140:141]
	v_pk_mul_f32 v[120:121], v[120:121], v[138:139]
	v_lshl_add_u64 v[166:167], v[130:131], 1, s[76:77]
	v_mul_f32_e32 v130, s11, v129
	v_pk_fma_f32 v[120:121], v[124:125], v[134:135], v[120:121]
	v_pk_fma_f32 v[122:123], v[126:127], v[136:137], v[122:123]
	v_mad_i64_i32 v[174:175], s[14:15], s74, v162, 0
	v_pk_fma_f32 v[178:179], v[124:125], v[138:139], v[178:179] neg_lo:[0,0,1] neg_hi:[0,0,1]
	v_pk_fma_f32 v[176:177], v[126:127], v[140:141], v[176:177] neg_lo:[0,0,1] neg_hi:[0,0,1]
	v_pk_mul_f32 v[124:125], v[130:131], v[122:123] op_sel_hi:[0,1]
	v_pk_mul_f32 v[122:123], v[130:131], v[120:121] op_sel_hi:[0,1]
	v_lshl_add_u64 v[174:175], v[174:175], 1, v[166:167]
	v_pk_mul_f32 v[176:177], v[130:131], v[176:177] op_sel_hi:[0,1]
	v_pk_mul_f32 v[178:179], v[130:131], v[178:179] op_sel_hi:[0,1]
	v_cvt_pk_bf16_f32 v120, v178, v179
	v_cvt_pk_bf16_f32 v121, v176, v177
	v_cvt_pk_bf16_f32 v122, v122, v123
	v_cvt_pk_bf16_f32 v123, v124, v125
	global_store_dwordx4 v[174:175], v[120:123], off
	v_mov_b32_e32 v133, 0
	v_mov_b32_e32 v129, 1.0
	v_pk_mul_f32 v[120:121], v[114:115], v[136:137]
	v_pk_mul_f32 v[122:123], v[112:113], v[134:135]
	v_pk_mul_f32 v[114:115], v[114:115], v[140:141]
	v_pk_mul_f32 v[112:113], v[112:113], v[138:139]
	v_pk_fma_f32 v[122:123], v[116:117], v[138:139], v[122:123] neg_lo:[0,0,1] neg_hi:[0,0,1]
	v_pk_fma_f32 v[112:113], v[116:117], v[134:135], v[112:113]
	v_pk_fma_f32 v[114:115], v[118:119], v[136:137], v[114:115]
	v_pk_fma_f32 v[120:121], v[118:119], v[140:141], v[120:121] neg_lo:[0,0,1] neg_hi:[0,0,1]
	v_pk_mul_f32 v[122:123], v[130:131], v[122:123] op_sel_hi:[0,1]
	v_pk_mul_f32 v[116:117], v[130:131], v[114:115] op_sel_hi:[0,1]
	v_pk_mul_f32 v[114:115], v[130:131], v[112:113] op_sel_hi:[0,1]
	v_cvt_pk_bf16_f32 v112, v122, v123
	v_pk_mul_f32 v[120:121], v[130:131], v[120:121] op_sel_hi:[0,1]
	v_cvt_pk_bf16_f32 v113, v120, v121
	v_cvt_pk_bf16_f32 v114, v114, v115
	v_cvt_pk_bf16_f32 v115, v116, v117
	global_store_dwordx4 v[174:175], v[112:115], off offset:256
	v_mov_b32_e32 v134, 0
	v_mov_b32_e32 v135, 0
	v_or_b32_e32 v112, 16, v162
	v_ashrrev_i32_e32 v113, 31, v112
	v_lshl_add_u64 v[114:115], v[112:113], 2, s[0:1]
	v_mov_b32_e32 v113, v181
	v_mov_b32_e32 v130, 1.0
	v_mov_b32_e32 v131, 1.0
	s_and_saveexec_b64 s[70:71], s[72:73]
	s_cbranch_execz .LBB0_402
	v_lshlrev_b32_e32 v114, 6, v112
	v_and_b32_e32 v150, 0x7f7c0, v114
	v_lshl_add_u64 v[114:115], v[152:153], 0, v[150:151]
	v_mov_b32_e32 v128, v196
	v_mov_b32_e32 v129, v197
	v_mov_b32_e32 v130, v198
	v_mov_b32_e32 v131, v199
	v_mov_b32_e32 v132, v200
	v_mov_b32_e32 v133, v201
	v_mov_b32_e32 v134, v202
	v_mov_b32_e32 v135, v203
	v_add_u32_e32 v204, 0x80, v162
	v_lshlrev_b32_e32 v204, 6, v204
	v_and_b32_e32 v150, 0x7ffc0, v204
	v_lshl_add_u64 v[204:205], v[152:153], 0, v[150:151]
	global_load_dwordx4 v[188:191], v[204:205], off offset:0
	global_load_dwordx4 v[192:195], v[204:205], off offset:32
	global_load_dwordx4 v[196:199], v[204:205], off offset:1024
	global_load_dwordx4 v[200:203], v[204:205], off offset:1056
; __device__ __forceinline__ u32x4 pack8(f32x4 a, f32x4 b) { u32x4 w; w.x = cvt_pk_bf16(a[0], a[1]); w.y = cvt_pk_bf16(a[2], a[3]); w.z = cvt_pk_bf16(b[0], b[1]); w.w = cvt_pk_bf16(b[2], b[3]); return w; }
;     __device__ __forceinline__ void operator()(const f32x4 (&acc)[2][2][4][2], const Unit& u, int wr, int wc, int fr, int fq) const {
;     ...
;                 const int row = row0 + ai * HALF + m * 16;
;                 const float rs = rs1[row] * sc;
;                 f32x4 cs = (f32x4){1.f, 1.f, 1.f, 1.f}, sn = (f32x4){0.f, 0.f, 0.f, 0.f};
;                 if (rl) { const float* rp = rope + (size_t)(row & (SEQ - 1)) * 16 + 4 * fq; cs = *(const f32x4*)rp; sn = *(const f32x4*)(rp + 8); }
;                 bf16_t* rowp = base + (size_t)row * ldc + col0;
; #pragma unroll
;                 for (int bj = 0; bj < 2; ++bj) {
;                     const f32x4 v0 = acc[ai][bj][m][0], v1 = acc[ai][bj][m][1];
;                     const f32x4 o0 = (v0 * cs - v1 * sn) * rs, o1 = (v1 * cs + v0 * sn) * rs;
;                     *(u32x4*)(rowp + bj * HALF) = pack8(o0, o1);
.LBB0_402:
	s_or_b64 exec, exec, s[70:71]
	v_pk_mul_f32 v[116:117], v[106:107], v[134:135]
	v_pk_mul_f32 v[118:119], v[104:105], v[132:133]
	v_pk_mul_f32 v[106:107], v[106:107], v[130:131]
	v_pk_mul_f32 v[104:105], v[104:105], v[128:129]
	v_mul_f32_e32 v114, s11, v113
	v_pk_fma_f32 v[104:105], v[108:109], v[132:133], v[104:105]
	v_pk_fma_f32 v[106:107], v[110:111], v[134:135], v[106:107]
	v_mad_i64_i32 v[112:113], s[14:15], s74, v112, 0
	v_pk_fma_f32 v[118:119], v[108:109], v[128:129], v[118:119] neg_lo:[0,0,1] neg_hi:[0,0,1]
	v_pk_fma_f32 v[116:117], v[110:111], v[130:131], v[116:117] neg_lo:[0,0,1] neg_hi:[0,0,1]
	v_pk_mul_f32 v[108:109], v[114:115], v[106:107] op_sel_hi:[0,1]
	v_pk_mul_f32 v[106:107], v[114:115], v[104:105] op_sel_hi:[0,1]
	v_lshl_add_u64 v[112:113], v[112:113], 1, v[166:167]
	v_pk_mul_f32 v[116:117], v[114:115], v[116:117] op_sel_hi:[0,1]
	v_pk_mul_f32 v[118:119], v[114:115], v[118:119] op_sel_hi:[0,1]
	v_cvt_pk_bf16_f32 v104, v118, v119
	v_cvt_pk_bf16_f32 v105, v116, v117
	v_cvt_pk_bf16_f32 v106, v106, v107
	v_cvt_pk_bf16_f32 v107, v108, v109
	global_store_dwordx4 v[112:113], v[104:107], off
	v_mov_b32_e32 v108, 1.0
	v_mov_b32_e32 v109, 1.0
	v_pk_mul_f32 v[104:105], v[98:99], v[134:135]
	v_pk_mul_f32 v[106:107], v[96:97], v[132:133]
	v_pk_mul_f32 v[98:99], v[98:99], v[130:131]
	v_pk_mul_f32 v[96:97], v[96:97], v[128:129]
	v_pk_fma_f32 v[98:99], v[102:103], v[134:135], v[98:99]
	v_pk_fma_f32 v[96:97], v[100:101], v[132:133], v[96:97]
	v_pk_fma_f32 v[106:107], v[100:101], v[128:129], v[106:107] neg_lo:[0,0,1] neg_hi:[0,0,1]
	v_pk_fma_f32 v[104:105], v[102:103], v[130:131], v[104:105] neg_lo:[0,0,1] neg_hi:[0,0,1]
	v_pk_mul_f32 v[100:101], v[114:115], v[98:99] op_sel_hi:[0,1]
	v_pk_mul_f32 v[98:99], v[114:115], v[96:97] op_sel_hi:[0,1]
	v_pk_mul_f32 v[104:105], v[114:115], v[104:105] op_sel_hi:[0,1]
	v_pk_mul_f32 v[106:107], v[114:115], v[106:107] op_sel_hi:[0,1]
	v_cvt_pk_bf16_f32 v96, v106, v107
	v_cvt_pk_bf16_f32 v97, v104, v105
	v_cvt_pk_bf16_f32 v98, v98, v99
	v_cvt_pk_bf16_f32 v99, v100, v101
	global_store_dwordx4 v[112:113], v[96:99], off offset:256
	v_mov_b32_e32 v100, 0
	v_mov_b32_e32 v102, 0
	v_or_b32_e32 v98, 32, v162
	v_ashrrev_i32_e32 v99, 31, v98
	v_lshl_add_u64 v[96:97], v[98:99], 2, s[0:1]
	v_mov_b32_e32 v97, v182
	v_mov_b32_e32 v96, 1.0
	v_mov_b32_e32 v103, 0
	v_mov_b32_e32 v104, 0
	v_mov_b32_e32 v105, 0
	v_mov_b32_e32 v106, 1.0
	v_mov_b32_e32 v107, 1.0
	s_and_saveexec_b64 s[70:71], s[72:73]
	s_cbranch_execz .LBB0_404
	v_lshlrev_b32_e32 v99, 6, v98
	v_and_b32_e32 v150, 0x7fbc0, v99
	v_lshl_add_u64 v[102:103], v[152:153], 0, v[150:151]
	v_mov_b32_e32 v106, v208
	v_mov_b32_e32 v107, v209
	v_mov_b32_e32 v108, v210
	v_mov_b32_e32 v109, v211
	v_mov_b32_e32 v102, v212
	v_mov_b32_e32 v103, v213
	v_mov_b32_e32 v104, v214
	v_mov_b32_e32 v105, v215
.LBB0_404:
	s_or_b64 exec, exec, s[70:71]
	v_pk_mul_f32 v[112:113], v[90:91], v[104:105]
	v_pk_mul_f32 v[114:115], v[88:89], v[102:103]
	v_pk_mul_f32 v[90:91], v[90:91], v[108:109]
	v_pk_mul_f32 v[88:89], v[88:89], v[106:107]
	v_mul_f32_e32 v110, s11, v97
	v_pk_fma_f32 v[88:89], v[92:93], v[102:103], v[88:89]
	v_pk_fma_f32 v[90:91], v[94:95], v[104:105], v[90:91]
	v_mad_i64_i32 v[98:99], s[14:15], s74, v98, 0
	v_pk_fma_f32 v[114:115], v[92:93], v[106:107], v[114:115] neg_lo:[0,0,1] neg_hi:[0,0,1]
	v_pk_fma_f32 v[112:113], v[94:95], v[108:109], v[112:113] neg_lo:[0,0,1] neg_hi:[0,0,1]
	v_pk_mul_f32 v[92:93], v[110:111], v[90:91] op_sel_hi:[0,1]
	v_pk_mul_f32 v[90:91], v[110:111], v[88:89] op_sel_hi:[0,1]
	v_lshl_add_u64 v[98:99], v[98:99], 1, v[166:167]
	v_pk_mul_f32 v[112:113], v[110:111], v[112:113] op_sel_hi:[0,1]
	v_pk_mul_f32 v[114:115], v[110:111], v[114:115] op_sel_hi:[0,1]
	v_cvt_pk_bf16_f32 v88, v114, v115
	v_cvt_pk_bf16_f32 v89, v112, v113
	v_cvt_pk_bf16_f32 v90, v90, v91
	v_cvt_pk_bf16_f32 v91, v92, v93
	global_store_dwordx4 v[98:99], v[88:91], off
	v_mov_b32_e32 v101, 0
	v_mov_b32_e32 v97, 1.0
	v_pk_mul_f32 v[88:89], v[82:83], v[104:105]
	v_pk_mul_f32 v[90:91], v[80:81], v[102:103]
	v_pk_mul_f32 v[82:83], v[82:83], v[108:109]
	v_pk_mul_f32 v[80:81], v[80:81], v[106:107]
	v_pk_fma_f32 v[90:91], v[84:85], v[106:107], v[90:91] neg_lo:[0,0,1] neg_hi:[0,0,1]
	v_pk_fma_f32 v[80:81], v[84:85], v[102:103], v[80:81]
	v_pk_fma_f32 v[82:83], v[86:87], v[104:105], v[82:83]
	v_pk_fma_f32 v[88:89], v[86:87], v[108:109], v[88:89] neg_lo:[0,0,1] neg_hi:[0,0,1]
	v_pk_mul_f32 v[90:91], v[110:111], v[90:91] op_sel_hi:[0,1]
	v_pk_mul_f32 v[84:85], v[110:111], v[82:83] op_sel_hi:[0,1]
	v_pk_mul_f32 v[82:83], v[110:111], v[80:81] op_sel_hi:[0,1]
	v_cvt_pk_bf16_f32 v80, v90, v91
	v_pk_mul_f32 v[88:89], v[110:111], v[88:89] op_sel_hi:[0,1]
	v_cvt_pk_bf16_f32 v81, v88, v89
	v_cvt_pk_bf16_f32 v82, v82, v83
	v_cvt_pk_bf16_f32 v83, v84, v85
	global_store_dwordx4 v[98:99], v[80:83], off offset:256
	v_mov_b32_e32 v102, 0
	v_mov_b32_e32 v103, 0
	v_or_b32_e32 v80, 48, v162
	v_ashrrev_i32_e32 v81, 31, v80
	v_lshl_add_u64 v[82:83], v[80:81], 2, s[0:1]
	v_mov_b32_e32 v81, v183
	v_mov_b32_e32 v98, 1.0
	v_mov_b32_e32 v99, 1.0
	s_and_saveexec_b64 s[70:71], s[72:73]
	s_cbranch_execz .LBB0_406
	v_lshlrev_b32_e32 v82, 6, v80
	v_and_b32_e32 v150, 0x7ffc0, v82
	v_lshl_add_u64 v[82:83], v[152:153], 0, v[150:151]
	v_mov_b32_e32 v96, v216
	v_mov_b32_e32 v97, v217
	v_mov_b32_e32 v98, v218
	v_mov_b32_e32 v99, v219
	v_mov_b32_e32 v100, v220
	v_mov_b32_e32 v101, v221
	v_mov_b32_e32 v102, v222
	v_mov_b32_e32 v103, v223
	global_load_dwordx4 v[208:211], v[204:205], off offset:2048
	global_load_dwordx4 v[212:215], v[204:205], off offset:2080
	global_load_dwordx4 v[216:219], v[204:205], off offset:3072
	global_load_dwordx4 v[220:223], v[204:205], off offset:3104
; __device__ __forceinline__ u32x4 pack8(f32x4 a, f32x4 b) { u32x4 w; w.x = cvt_pk_bf16(a[0], a[1]); w.y = cvt_pk_bf16(a[2], a[3]); w.z = cvt_pk_bf16(b[0], b[1]); w.w = cvt_pk_bf16(b[2], b[3]); return w; }
;     __device__ __forceinline__ void operator()(const f32x4 (&acc)[2][2][4][2], const Unit& u, int wr, int wc, int fr, int fq) const {
;     ...
;                 const int row = row0 + ai * HALF + m * 16;
;                 const float rs = rs1[row] * sc;
;                 f32x4 cs = (f32x4){1.f, 1.f, 1.f, 1.f}, sn = (f32x4){0.f, 0.f, 0.f, 0.f};
;                 if (rl) { const float* rp = rope + (size_t)(row & (SEQ - 1)) * 16 + 4 * fq; cs = *(const f32x4*)rp; sn = *(const f32x4*)(rp + 8); }
;                 bf16_t* rowp = base + (size_t)row * ldc + col0;
; #pragma unroll
;                 for (int bj = 0; bj < 2; ++bj) {
;                     const f32x4 v0 = acc[ai][bj][m][0], v1 = acc[ai][bj][m][1];
;                     const f32x4 o0 = (v0 * cs - v1 * sn) * rs, o1 = (v1 * cs + v0 * sn) * rs;
;                     *(u32x4*)(rowp + bj * HALF) = pack8(o0, o1);
.LBB0_406:
	s_or_b64 exec, exec, s[70:71]
	v_pk_mul_f32 v[84:85], v[74:75], v[102:103]
	v_pk_mul_f32 v[86:87], v[72:73], v[100:101]
	v_pk_mul_f32 v[74:75], v[74:75], v[98:99]
	v_pk_mul_f32 v[72:73], v[72:73], v[96:97]
	v_mul_f32_e32 v82, s11, v81
	v_pk_fma_f32 v[72:73], v[76:77], v[100:101], v[72:73]
	v_pk_fma_f32 v[74:75], v[78:79], v[102:103], v[74:75]
	v_mad_i64_i32 v[80:81], s[14:15], s74, v80, 0
	v_pk_fma_f32 v[86:87], v[76:77], v[96:97], v[86:87] neg_lo:[0,0,1] neg_hi:[0,0,1]
	v_pk_fma_f32 v[84:85], v[78:79], v[98:99], v[84:85] neg_lo:[0,0,1] neg_hi:[0,0,1]
	v_pk_mul_f32 v[76:77], v[82:83], v[74:75] op_sel_hi:[0,1]
	v_pk_mul_f32 v[74:75], v[82:83], v[72:73] op_sel_hi:[0,1]
	v_lshl_add_u64 v[80:81], v[80:81], 1, v[166:167]
	v_pk_mul_f32 v[84:85], v[82:83], v[84:85] op_sel_hi:[0,1]
	v_pk_mul_f32 v[86:87], v[82:83], v[86:87] op_sel_hi:[0,1]
	v_cvt_pk_bf16_f32 v72, v86, v87
	v_cvt_pk_bf16_f32 v73, v84, v85
	v_cvt_pk_bf16_f32 v74, v74, v75
	v_cvt_pk_bf16_f32 v75, v76, v77
	global_store_dwordx4 v[80:81], v[72:75], off
	v_mov_b32_e32 v76, 1.0
	v_mov_b32_e32 v77, 1.0
	v_pk_mul_f32 v[72:73], v[66:67], v[102:103]
	v_pk_mul_f32 v[74:75], v[64:65], v[100:101]
	v_pk_mul_f32 v[66:67], v[66:67], v[98:99]
	v_pk_mul_f32 v[64:65], v[64:65], v[96:97]
	v_pk_fma_f32 v[66:67], v[70:71], v[102:103], v[66:67]
	v_pk_fma_f32 v[64:65], v[68:69], v[100:101], v[64:65]
	v_pk_fma_f32 v[74:75], v[68:69], v[96:97], v[74:75] neg_lo:[0,0,1] neg_hi:[0,0,1]
	v_pk_fma_f32 v[72:73], v[70:71], v[98:99], v[72:73] neg_lo:[0,0,1] neg_hi:[0,0,1]
	v_pk_mul_f32 v[68:69], v[82:83], v[66:67] op_sel_hi:[0,1]
	v_pk_mul_f32 v[66:67], v[82:83], v[64:65] op_sel_hi:[0,1]
	v_pk_mul_f32 v[72:73], v[82:83], v[72:73] op_sel_hi:[0,1]
	v_pk_mul_f32 v[74:75], v[82:83], v[74:75] op_sel_hi:[0,1]
	v_cvt_pk_bf16_f32 v64, v74, v75
	v_cvt_pk_bf16_f32 v65, v72, v73
	v_cvt_pk_bf16_f32 v66, v66, v67
	v_cvt_pk_bf16_f32 v67, v68, v69
	global_store_dwordx4 v[80:81], v[64:67], off offset:256
	s_nop 1
	v_mov_b32_e32 v65, v184
	v_mov_b32_e32 v68, 0
	v_add_u32_e32 v66, 0x80, v162
	v_mov_b32_e32 v64, 1.0
	v_mov_b32_e32 v70, 0
	v_mov_b32_e32 v71, 0
	v_mov_b32_e32 v72, 0
	v_mov_b32_e32 v73, 0
	v_mov_b32_e32 v74, 1.0
	v_mov_b32_e32 v75, 1.0
	s_and_saveexec_b64 s[70:71], s[72:73]
	s_cbranch_execz .LBB0_408
	v_lshlrev_b32_e32 v67, 6, v66
	v_and_b32_e32 v150, 0x7f3c0, v67
	v_lshl_add_u64 v[70:71], v[152:153], 0, v[150:151]
	s_waitcnt vmcnt(10)
	v_mov_b32_e32 v74, v188
	v_mov_b32_e32 v75, v189
	v_mov_b32_e32 v76, v190
	v_mov_b32_e32 v77, v191
	v_mov_b32_e32 v70, v192
	v_mov_b32_e32 v71, v193
	v_mov_b32_e32 v72, v194
	v_mov_b32_e32 v73, v195
.LBB0_408:
	s_or_b64 exec, exec, s[70:71]
	v_pk_mul_f32 v[80:81], v[58:59], v[72:73]
	v_pk_mul_f32 v[82:83], v[56:57], v[70:71]
	v_pk_mul_f32 v[58:59], v[58:59], v[76:77]
	v_pk_mul_f32 v[56:57], v[56:57], v[74:75]
	v_mul_f32_e32 v78, s11, v65
	v_pk_fma_f32 v[56:57], v[60:61], v[70:71], v[56:57]
	v_pk_fma_f32 v[58:59], v[62:63], v[72:73], v[58:59]
	v_mad_i64_i32 v[66:67], s[14:15], s74, v66, 0
	v_pk_fma_f32 v[82:83], v[60:61], v[74:75], v[82:83] neg_lo:[0,0,1] neg_hi:[0,0,1]
	v_pk_fma_f32 v[80:81], v[62:63], v[76:77], v[80:81] neg_lo:[0,0,1] neg_hi:[0,0,1]
	v_pk_mul_f32 v[60:61], v[78:79], v[58:59] op_sel_hi:[0,1]
	v_pk_mul_f32 v[58:59], v[78:79], v[56:57] op_sel_hi:[0,1]
	v_lshl_add_u64 v[66:67], v[66:67], 1, v[166:167]
	v_pk_mul_f32 v[80:81], v[78:79], v[80:81] op_sel_hi:[0,1]
	v_pk_mul_f32 v[82:83], v[78:79], v[82:83] op_sel_hi:[0,1]
	v_cvt_pk_bf16_f32 v56, v82, v83
	v_cvt_pk_bf16_f32 v57, v80, v81
	v_cvt_pk_bf16_f32 v58, v58, v59
	v_cvt_pk_bf16_f32 v59, v60, v61
	global_store_dwordx4 v[66:67], v[56:59], off
	v_mov_b32_e32 v69, 0
	v_mov_b32_e32 v65, 1.0
	v_pk_mul_f32 v[56:57], v[50:51], v[72:73]
	v_pk_mul_f32 v[58:59], v[48:49], v[70:71]
	v_pk_mul_f32 v[50:51], v[50:51], v[76:77]
	v_pk_mul_f32 v[48:49], v[48:49], v[74:75]
	v_pk_fma_f32 v[50:51], v[54:55], v[72:73], v[50:51]
	v_pk_fma_f32 v[48:49], v[52:53], v[70:71], v[48:49]
	v_pk_fma_f32 v[58:59], v[52:53], v[74:75], v[58:59] neg_lo:[0,0,1] neg_hi:[0,0,1]
	v_pk_fma_f32 v[56:57], v[54:55], v[76:77], v[56:57] neg_lo:[0,0,1] neg_hi:[0,0,1]
	v_pk_mul_f32 v[52:53], v[78:79], v[50:51] op_sel_hi:[0,1]
	v_pk_mul_f32 v[50:51], v[78:79], v[48:49] op_sel_hi:[0,1]
	v_pk_mul_f32 v[56:57], v[78:79], v[56:57] op_sel_hi:[0,1]
	v_pk_mul_f32 v[58:59], v[78:79], v[58:59] op_sel_hi:[0,1]
	v_cvt_pk_bf16_f32 v48, v58, v59
	v_cvt_pk_bf16_f32 v49, v56, v57
	v_cvt_pk_bf16_f32 v50, v50, v51
	v_cvt_pk_bf16_f32 v51, v52, v53
	global_store_dwordx4 v[66:67], v[48:51], off offset:256
	s_nop 1
	v_mov_b32_e32 v48, v185
	v_mov_b32_e32 v70, 0
	v_add_u32_e32 v49, 0x90, v162
	v_mov_b32_e32 v71, 0
	v_mov_b32_e32 v66, 1.0
	v_mov_b32_e32 v67, 1.0
	s_and_saveexec_b64 s[70:71], s[72:73]
	s_cbranch_execz .LBB0_410
	v_lshlrev_b32_e32 v50, 6, v49
	v_and_b32_e32 v150, 0x7f7c0, v50
	v_lshl_add_u64 v[50:51], v[152:153], 0, v[150:151]
	v_mov_b32_e32 v64, v196
	v_mov_b32_e32 v65, v197
	v_mov_b32_e32 v66, v198
	v_mov_b32_e32 v67, v199
	v_mov_b32_e32 v68, v200
	v_mov_b32_e32 v69, v201
	v_mov_b32_e32 v70, v202
	v_mov_b32_e32 v71, v203
; __device__ __forceinline__ u32x4 pack8(f32x4 a, f32x4 b) { u32x4 w; w.x = cvt_pk_bf16(a[0], a[1]); w.y = cvt_pk_bf16(a[2], a[3]); w.z = cvt_pk_bf16(b[0], b[1]); w.w = cvt_pk_bf16(b[2], b[3]); return w; }
;     __device__ __forceinline__ void operator()(const f32x4 (&acc)[2][2][4][2], const Unit& u, int wr, int wc, int fr, int fq) const {
;     ...
;                 const int row = row0 + ai * HALF + m * 16;
;                 const float rs = rs1[row] * sc;
;                 f32x4 cs = (f32x4){1.f, 1.f, 1.f, 1.f}, sn = (f32x4){0.f, 0.f, 0.f, 0.f};
;                 if (rl) { const float* rp = rope + (size_t)(row & (SEQ - 1)) * 16 + 4 * fq; cs = *(const f32x4*)rp; sn = *(const f32x4*)(rp + 8); }
;                 bf16_t* rowp = base + (size_t)row * ldc + col0;
; #pragma unroll
;                 for (int bj = 0; bj < 2; ++bj) {
;                     const f32x4 v0 = acc[ai][bj][m][0], v1 = acc[ai][bj][m][1];
;                     const f32x4 o0 = (v0 * cs - v1 * sn) * rs, o1 = (v1 * cs + v0 * sn) * rs;
;                     *(u32x4*)(rowp + bj * HALF) = pack8(o0, o1);
.LBB0_410:
	s_or_b64 exec, exec, s[70:71]
	v_pk_mul_f32 v[52:53], v[42:43], v[70:71]
	v_pk_mul_f32 v[54:55], v[40:41], v[68:69]
	v_pk_mul_f32 v[42:43], v[42:43], v[66:67]
	v_pk_mul_f32 v[40:41], v[40:41], v[64:65]
	v_mul_f32_e32 v48, s11, v48
	v_pk_fma_f32 v[40:41], v[44:45], v[68:69], v[40:41]
	v_pk_fma_f32 v[42:43], v[46:47], v[70:71], v[42:43]
	v_mad_i64_i32 v[50:51], s[14:15], s74, v49, 0
	v_pk_fma_f32 v[54:55], v[44:45], v[64:65], v[54:55] neg_lo:[0,0,1] neg_hi:[0,0,1]
	v_pk_fma_f32 v[52:53], v[46:47], v[66:67], v[52:53] neg_lo:[0,0,1] neg_hi:[0,0,1]
	v_pk_mul_f32 v[44:45], v[48:49], v[42:43] op_sel_hi:[0,1]
	v_pk_mul_f32 v[42:43], v[48:49], v[40:41] op_sel_hi:[0,1]
	v_lshl_add_u64 v[50:51], v[50:51], 1, v[166:167]
	v_pk_mul_f32 v[52:53], v[48:49], v[52:53] op_sel_hi:[0,1]
	v_pk_mul_f32 v[54:55], v[48:49], v[54:55] op_sel_hi:[0,1]
	v_cvt_pk_bf16_f32 v40, v54, v55
	v_cvt_pk_bf16_f32 v41, v52, v53
	v_cvt_pk_bf16_f32 v42, v42, v43
	v_cvt_pk_bf16_f32 v43, v44, v45
	global_store_dwordx4 v[50:51], v[40:43], off
	v_mov_b32_e32 v44, 1.0
	v_mov_b32_e32 v45, 1.0
	v_pk_mul_f32 v[40:41], v[34:35], v[70:71]
	v_pk_mul_f32 v[42:43], v[32:33], v[68:69]
	v_pk_mul_f32 v[34:35], v[34:35], v[66:67]
	v_pk_mul_f32 v[32:33], v[32:33], v[64:65]
	v_pk_fma_f32 v[34:35], v[38:39], v[70:71], v[34:35]
	v_pk_fma_f32 v[32:33], v[36:37], v[68:69], v[32:33]
	v_pk_fma_f32 v[42:43], v[36:37], v[64:65], v[42:43] neg_lo:[0,0,1] neg_hi:[0,0,1]
	v_pk_fma_f32 v[40:41], v[38:39], v[66:67], v[40:41] neg_lo:[0,0,1] neg_hi:[0,0,1]
	v_pk_mul_f32 v[36:37], v[48:49], v[34:35] op_sel_hi:[0,1]
	v_pk_mul_f32 v[34:35], v[48:49], v[32:33] op_sel_hi:[0,1]
	v_pk_mul_f32 v[40:41], v[48:49], v[40:41] op_sel_hi:[0,1]
	v_pk_mul_f32 v[42:43], v[48:49], v[42:43] op_sel_hi:[0,1]
	v_cvt_pk_bf16_f32 v32, v42, v43
	v_cvt_pk_bf16_f32 v33, v40, v41
	v_cvt_pk_bf16_f32 v34, v34, v35
	v_cvt_pk_bf16_f32 v35, v36, v37
	global_store_dwordx4 v[50:51], v[32:35], off offset:256
	s_nop 1
	v_mov_b32_e32 v33, v186
	v_mov_b32_e32 v36, 0
	v_add_u32_e32 v34, 0xa0, v162
	v_mov_b32_e32 v32, 1.0
	v_mov_b32_e32 v38, 0
	v_mov_b32_e32 v39, 0
	v_mov_b32_e32 v40, 0
	v_mov_b32_e32 v41, 0
	v_mov_b32_e32 v42, 1.0
	v_mov_b32_e32 v43, 1.0
	s_and_saveexec_b64 s[70:71], s[72:73]
	s_cbranch_execz .LBB0_412
	v_lshlrev_b32_e32 v35, 6, v34
	v_and_b32_e32 v150, 0x7fbc0, v35
	v_lshl_add_u64 v[38:39], v[152:153], 0, v[150:151]
	s_waitcnt vmcnt(6)
	v_mov_b32_e32 v42, v208
	v_mov_b32_e32 v43, v209
	v_mov_b32_e32 v44, v210
	v_mov_b32_e32 v45, v211
	v_mov_b32_e32 v38, v212
	v_mov_b32_e32 v39, v213
	v_mov_b32_e32 v40, v214
	v_mov_b32_e32 v41, v215
; __device__ __forceinline__ u32x4 pack8(f32x4 a, f32x4 b) { u32x4 w; w.x = cvt_pk_bf16(a[0], a[1]); w.y = cvt_pk_bf16(a[2], a[3]); w.z = cvt_pk_bf16(b[0], b[1]); w.w = cvt_pk_bf16(b[2], b[3]); return w; }
;     __device__ __forceinline__ void operator()(const f32x4 (&acc)[2][2][4][2], const Unit& u, int wr, int wc, int fr, int fq) const {
;     ...
;                 const int row = row0 + ai * HALF + m * 16;
;                 const float rs = rs1[row] * sc;
;                 f32x4 cs = (f32x4){1.f, 1.f, 1.f, 1.f}, sn = (f32x4){0.f, 0.f, 0.f, 0.f};
;                 if (rl) { const float* rp = rope + (size_t)(row & (SEQ - 1)) * 16 + 4 * fq; cs = *(const f32x4*)rp; sn = *(const f32x4*)(rp + 8); }
;                 bf16_t* rowp = base + (size_t)row * ldc + col0;
; #pragma unroll
;                 for (int bj = 0; bj < 2; ++bj) {
;                     const f32x4 v0 = acc[ai][bj][m][0], v1 = acc[ai][bj][m][1];
;                     const f32x4 o0 = (v0 * cs - v1 * sn) * rs, o1 = (v1 * cs + v0 * sn) * rs;
;                     *(u32x4*)(rowp + bj * HALF) = pack8(o0, o1);
;                 }
;             }
.LBB0_412:
	s_or_b64 exec, exec, s[70:71]
	v_pk_mul_f32 v[48:49], v[26:27], v[40:41]
	v_pk_mul_f32 v[50:51], v[24:25], v[38:39]
	v_pk_mul_f32 v[26:27], v[26:27], v[44:45]
	v_pk_mul_f32 v[24:25], v[24:25], v[42:43]
	v_mul_f32_e32 v46, s11, v33
	v_pk_fma_f32 v[24:25], v[28:29], v[38:39], v[24:25]
	v_pk_fma_f32 v[26:27], v[30:31], v[40:41], v[26:27]
	v_mad_i64_i32 v[34:35], s[14:15], s74, v34, 0
	v_pk_fma_f32 v[50:51], v[28:29], v[42:43], v[50:51] neg_lo:[0,0,1] neg_hi:[0,0,1]
	v_pk_fma_f32 v[48:49], v[30:31], v[44:45], v[48:49] neg_lo:[0,0,1] neg_hi:[0,0,1]
	v_pk_mul_f32 v[28:29], v[46:47], v[26:27] op_sel_hi:[0,1]
	v_pk_mul_f32 v[26:27], v[46:47], v[24:25] op_sel_hi:[0,1]
	v_lshl_add_u64 v[34:35], v[34:35], 1, v[166:167]
	v_pk_mul_f32 v[48:49], v[46:47], v[48:49] op_sel_hi:[0,1]
	v_pk_mul_f32 v[50:51], v[46:47], v[50:51] op_sel_hi:[0,1]
	v_cvt_pk_bf16_f32 v24, v50, v51
	v_cvt_pk_bf16_f32 v25, v48, v49
	v_cvt_pk_bf16_f32 v26, v26, v27
	v_cvt_pk_bf16_f32 v27, v28, v29
	global_store_dwordx4 v[34:35], v[24:27], off
	v_mov_b32_e32 v37, 0
	v_mov_b32_e32 v33, 1.0
	v_pk_mul_f32 v[24:25], v[18:19], v[40:41]
	v_pk_mul_f32 v[26:27], v[16:17], v[38:39]
	v_pk_mul_f32 v[18:19], v[18:19], v[44:45]
	v_pk_mul_f32 v[16:17], v[16:17], v[42:43]
	v_pk_fma_f32 v[18:19], v[22:23], v[40:41], v[18:19]
	v_pk_fma_f32 v[16:17], v[20:21], v[38:39], v[16:17]
	v_pk_fma_f32 v[26:27], v[20:21], v[42:43], v[26:27] neg_lo:[0,0,1] neg_hi:[0,0,1]
	v_pk_fma_f32 v[24:25], v[22:23], v[44:45], v[24:25] neg_lo:[0,0,1] neg_hi:[0,0,1]
	v_pk_mul_f32 v[20:21], v[46:47], v[18:19] op_sel_hi:[0,1]
	v_pk_mul_f32 v[18:19], v[46:47], v[16:17] op_sel_hi:[0,1]
	v_pk_mul_f32 v[24:25], v[46:47], v[24:25] op_sel_hi:[0,1]
	v_pk_mul_f32 v[26:27], v[46:47], v[26:27] op_sel_hi:[0,1]
	v_cvt_pk_bf16_f32 v16, v26, v27
	v_cvt_pk_bf16_f32 v17, v24, v25
	v_cvt_pk_bf16_f32 v18, v18, v19
	v_cvt_pk_bf16_f32 v19, v20, v21
	global_store_dwordx4 v[34:35], v[16:19], off offset:256
	s_nop 1
	v_mov_b32_e32 v16, v187
	v_mov_b32_e32 v38, 0
	v_add_u32_e32 v17, 0xb0, v162
	v_mov_b32_e32 v39, 0
	v_mov_b32_e32 v34, 1.0
	v_mov_b32_e32 v35, 1.0
	s_and_saveexec_b64 s[70:71], s[72:73]
	s_cbranch_execz .LBB0_414
	v_lshlrev_b32_e32 v18, 6, v17
	v_and_b32_e32 v150, 0x7ffc0, v18
	v_lshl_add_u64 v[18:19], v[152:153], 0, v[150:151]
	v_mov_b32_e32 v32, v216
	v_mov_b32_e32 v33, v217
	v_mov_b32_e32 v34, v218
	v_mov_b32_e32 v35, v219
	v_mov_b32_e32 v36, v220
	v_mov_b32_e32 v37, v221
	v_mov_b32_e32 v38, v222
	v_mov_b32_e32 v39, v223
.LBB0_414:
	s_or_b64 exec, exec, s[70:71]
	v_pk_mul_f32 v[20:21], v[10:11], v[38:39]
	v_pk_mul_f32 v[22:23], v[8:9], v[36:37]
	v_pk_mul_f32 v[10:11], v[10:11], v[34:35]
	v_pk_mul_f32 v[8:9], v[8:9], v[32:33]
	v_mul_f32_e32 v16, s11, v16
	v_pk_fma_f32 v[8:9], v[12:13], v[36:37], v[8:9]
	v_pk_fma_f32 v[10:11], v[14:15], v[38:39], v[10:11]
	v_mad_i64_i32 v[18:19], s[14:15], s74, v17, 0
	v_pk_fma_f32 v[22:23], v[12:13], v[32:33], v[22:23] neg_lo:[0,0,1] neg_hi:[0,0,1]
	v_pk_fma_f32 v[20:21], v[14:15], v[34:35], v[20:21] neg_lo:[0,0,1] neg_hi:[0,0,1]
	v_pk_mul_f32 v[12:13], v[16:17], v[10:11] op_sel_hi:[0,1]
	v_pk_mul_f32 v[10:11], v[16:17], v[8:9] op_sel_hi:[0,1]
	v_lshl_add_u64 v[18:19], v[18:19], 1, v[166:167]
	v_pk_mul_f32 v[20:21], v[16:17], v[20:21] op_sel_hi:[0,1]
	v_pk_mul_f32 v[22:23], v[16:17], v[22:23] op_sel_hi:[0,1]
	v_cvt_pk_bf16_f32 v8, v22, v23
	v_cvt_pk_bf16_f32 v9, v20, v21
	v_cvt_pk_bf16_f32 v10, v10, v11
	v_cvt_pk_bf16_f32 v11, v12, v13
	global_store_dwordx4 v[18:19], v[8:11], off
	s_andn2_b64 vcc, exec, s[4:5]
	s_mov_b64 s[4:5], -1
	v_pk_mul_f32 v[8:9], v[2:3], v[38:39]
	v_pk_mul_f32 v[10:11], v[0:1], v[36:37]
	v_pk_mul_f32 v[2:3], v[2:3], v[34:35]
	v_pk_mul_f32 v[0:1], v[0:1], v[32:33]
	v_pk_fma_f32 v[2:3], v[6:7], v[38:39], v[2:3]
	v_pk_fma_f32 v[0:1], v[4:5], v[36:37], v[0:1]
	v_pk_fma_f32 v[10:11], v[4:5], v[32:33], v[10:11] neg_lo:[0,0,1] neg_hi:[0,0,1]
	v_pk_fma_f32 v[8:9], v[6:7], v[34:35], v[8:9] neg_lo:[0,0,1] neg_hi:[0,0,1]
	v_pk_mul_f32 v[4:5], v[16:17], v[2:3] op_sel_hi:[0,1]
	v_pk_mul_f32 v[2:3], v[16:17], v[0:1] op_sel_hi:[0,1]
	v_pk_mul_f32 v[8:9], v[16:17], v[8:9] op_sel_hi:[0,1]
	v_pk_mul_f32 v[10:11], v[16:17], v[10:11] op_sel_hi:[0,1]
	v_cvt_pk_bf16_f32 v0, v10, v11
	v_cvt_pk_bf16_f32 v1, v8, v9
	v_cvt_pk_bf16_f32 v2, v2, v3
	v_cvt_pk_bf16_f32 v3, v4, v5
	global_store_dwordx4 v[18:19], v[0:3], off offset:256
	s_cbranch_vccnz .LBB0_388
	s_andn2_b64 vcc, exec, s[42:43]
	s_cbranch_vccnz .LBB0_387
	s_barrier
	s_branch .LBB0_387
